# plus: NSA K-tile LDS swizzle widened to (row&15)<<4 (conflict-free ds_read_b128 lane groups) on top of spread LDS writes, late loads and batched stage-out
# speedup vs baseline: 1.0064x; 1.0019x over previous
; DI unsigned short f2bf1(float f) { return (unsigned short)(cvtpk(f, 0.f) & 0xffffu); }
; #define LDS_WAIT() asm volatile("s_waitcnt lgkmcnt(0)" ::: "memory")
; DI int crow(int r, int hi) { return (r & 3) + 8 * (r >> 2) + 4 * hi; }
; DI void nsa_stage_out(att::Core<128>& c, bf16_t* stg, float* ws, float fac, bool first, int r32, int hi) {
;     if (hi == 0) ws[r32] = fac;
;     LDS_WAIT();
; #pragma unroll
;     for (int r = 0; r < 16; ++r) { const int orow = att::crow(r, hi); const float f = ws[orow];
; #pragma unroll
;         for (int d0 = 0; d0 < 4; ++d0) { bf16_t* p = stg + orow * 136 + d0 * 32 + r32; float v = c.o[d0][r] * f; if (!first) v += bf2f(*p); *p = f2bf1(v); } }
;     LDS_WAIT();
; }
.LBB0_879:
	s_or_b64 exec, exec, s[2:3]
	s_waitcnt lgkmcnt(0)
	ds_read_b32 v86, v182
	ds_read_b32 v87, v182 offset:4
	ds_read_u16 v203, v199
	ds_read_u16 v204, v199 offset:64
	ds_read_u16 v205, v199 offset:128
	ds_read_u16 v206, v199 offset:192
	ds_read_u16 v207, v200
	ds_read_u16 v208, v200 offset:64
	ds_read_u16 v209, v200 offset:128
	ds_read_u16 v210, v200 offset:192
	s_waitcnt lgkmcnt(0)
	v_lshlrev_b32_e32 v203, 16, v203
	v_lshlrev_b32_e32 v204, 16, v204
	v_lshlrev_b32_e32 v205, 16, v205
	v_lshlrev_b32_e32 v206, 16, v206
	v_lshlrev_b32_e32 v207, 16, v207
	v_lshlrev_b32_e32 v208, 16, v208
	v_lshlrev_b32_e32 v209, 16, v209
	v_lshlrev_b32_e32 v210, 16, v210
	v_fmac_f32_e32 v203, v50, v86
	v_fmac_f32_e32 v204, v34, v86
	v_fmac_f32_e32 v205, v18, v86
	v_fmac_f32_e32 v206, v2, v86
	v_fmac_f32_e32 v207, v51, v87
	v_fmac_f32_e32 v208, v35, v87
	v_fmac_f32_e32 v209, v19, v87
	v_fmac_f32_e32 v210, v3, v87
	v_cvt_pk_bf16_f32 v203, v203, v1
	v_cvt_pk_bf16_f32 v204, v204, v1
	v_cvt_pk_bf16_f32 v205, v205, v1
	v_cvt_pk_bf16_f32 v206, v206, v1
	v_cvt_pk_bf16_f32 v207, v207, v1
	v_cvt_pk_bf16_f32 v208, v208, v1
	v_cvt_pk_bf16_f32 v209, v209, v1
	v_cvt_pk_bf16_f32 v210, v210, v1
	ds_write_b16 v199, v203
	ds_write_b16 v199, v204 offset:64
	ds_write_b16 v199, v205 offset:128
	ds_write_b16 v199, v206 offset:192
	ds_write_b16 v200, v207
	ds_write_b16 v200, v208 offset:64
	ds_write_b16 v200, v209 offset:128
	ds_write_b16 v200, v210 offset:192
	s_waitcnt lgkmcnt(5)
	ds_read_b32 v86, v182 offset:8
	ds_read_b32 v87, v182 offset:12
	ds_read_u16 v203, v200 offset:272
	ds_read_u16 v204, v200 offset:336
	ds_read_u16 v205, v200 offset:400
	ds_read_u16 v206, v200 offset:464
	ds_read_u16 v207, v200 offset:544
	ds_read_u16 v208, v200 offset:608
	ds_read_u16 v209, v200 offset:672
	ds_read_u16 v210, v200 offset:736
	s_waitcnt lgkmcnt(0)
	v_lshlrev_b32_e32 v203, 16, v203
	v_lshlrev_b32_e32 v204, 16, v204
	v_lshlrev_b32_e32 v205, 16, v205
	v_lshlrev_b32_e32 v206, 16, v206
	v_lshlrev_b32_e32 v207, 16, v207
	v_lshlrev_b32_e32 v208, 16, v208
	v_lshlrev_b32_e32 v209, 16, v209
	v_lshlrev_b32_e32 v210, 16, v210
	v_fmac_f32_e32 v203, v52, v86
	v_fmac_f32_e32 v204, v36, v86
	v_fmac_f32_e32 v205, v20, v86
	v_fmac_f32_e32 v206, v4, v86
	v_fmac_f32_e32 v207, v53, v87
	v_fmac_f32_e32 v208, v37, v87
	v_fmac_f32_e32 v209, v21, v87
	v_fmac_f32_e32 v210, v5, v87
	v_cvt_pk_bf16_f32 v203, v203, v1
	v_cvt_pk_bf16_f32 v204, v204, v1
	v_cvt_pk_bf16_f32 v205, v205, v1
	v_cvt_pk_bf16_f32 v206, v206, v1
	v_cvt_pk_bf16_f32 v207, v207, v1
	v_cvt_pk_bf16_f32 v208, v208, v1
	v_cvt_pk_bf16_f32 v209, v209, v1
	v_cvt_pk_bf16_f32 v210, v210, v1
	ds_write_b16 v200, v203 offset:272
	ds_write_b16 v200, v204 offset:336
	ds_write_b16 v200, v205 offset:400
	ds_write_b16 v200, v206 offset:464
	ds_write_b16 v200, v207 offset:544
	ds_write_b16 v200, v208 offset:608
	ds_write_b16 v200, v209 offset:672
	ds_write_b16 v200, v210 offset:736
	s_waitcnt lgkmcnt(5)
	ds_read_b32 v86, v182 offset:32
	ds_read_b32 v87, v182 offset:36
	ds_read_u16 v203, v200 offset:1904
	ds_read_u16 v204, v200 offset:1968
	ds_read_u16 v205, v200 offset:2032
	ds_read_u16 v206, v200 offset:2096
	ds_read_u16 v207, v200 offset:2176
	ds_read_u16 v208, v200 offset:2240
	ds_read_u16 v209, v200 offset:2304
	ds_read_u16 v210, v200 offset:2368
	s_waitcnt lgkmcnt(0)
	v_lshlrev_b32_e32 v203, 16, v203
	v_lshlrev_b32_e32 v204, 16, v204
	v_lshlrev_b32_e32 v205, 16, v205
	v_lshlrev_b32_e32 v206, 16, v206
	v_lshlrev_b32_e32 v207, 16, v207
	v_lshlrev_b32_e32 v208, 16, v208
	v_lshlrev_b32_e32 v209, 16, v209
	v_lshlrev_b32_e32 v210, 16, v210
	v_fmac_f32_e32 v203, v54, v86
	v_fmac_f32_e32 v204, v38, v86
	v_fmac_f32_e32 v205, v22, v86
	v_fmac_f32_e32 v206, v6, v86
	v_fmac_f32_e32 v207, v55, v87
	v_fmac_f32_e32 v208, v39, v87
	v_fmac_f32_e32 v209, v23, v87
	v_fmac_f32_e32 v210, v7, v87
	v_cvt_pk_bf16_f32 v203, v203, v1
	v_cvt_pk_bf16_f32 v204, v204, v1
	v_cvt_pk_bf16_f32 v205, v205, v1
	v_cvt_pk_bf16_f32 v206, v206, v1
	v_cvt_pk_bf16_f32 v207, v207, v1
	v_cvt_pk_bf16_f32 v208, v208, v1
	v_cvt_pk_bf16_f32 v209, v209, v1
	v_cvt_pk_bf16_f32 v210, v210, v1
	ds_write_b16 v200, v203 offset:1904
	ds_write_b16 v200, v204 offset:1968
	ds_write_b16 v200, v205 offset:2032
	ds_write_b16 v200, v206 offset:2096
	ds_write_b16 v200, v207 offset:2176
	ds_write_b16 v200, v208 offset:2240
	ds_write_b16 v200, v209 offset:2304
	ds_write_b16 v200, v210 offset:2368
	s_waitcnt lgkmcnt(5)
	ds_read_b32 v86, v182 offset:40
	ds_read_b32 v87, v182 offset:44
	ds_read_u16 v203, v200 offset:2448
	ds_read_u16 v204, v201 offset:64
	ds_read_u16 v205, v201 offset:128
	ds_read_u16 v206, v201 offset:192
	ds_read_u16 v207, v201 offset:272
	ds_read_u16 v208, v201 offset:336
	ds_read_u16 v209, v201 offset:400
	ds_read_u16 v210, v201 offset:464
	s_waitcnt lgkmcnt(0)
	v_lshlrev_b32_e32 v203, 16, v203
	v_lshlrev_b32_e32 v204, 16, v204
	v_lshlrev_b32_e32 v205, 16, v205
	v_lshlrev_b32_e32 v206, 16, v206
	v_lshlrev_b32_e32 v207, 16, v207
	v_lshlrev_b32_e32 v208, 16, v208
	v_lshlrev_b32_e32 v209, 16, v209
	v_lshlrev_b32_e32 v210, 16, v210
	v_fmac_f32_e32 v203, v56, v86
	v_fmac_f32_e32 v204, v40, v86
	v_fmac_f32_e32 v205, v24, v86
	v_fmac_f32_e32 v206, v8, v86
	v_fmac_f32_e32 v207, v57, v87
	v_fmac_f32_e32 v208, v41, v87
	v_fmac_f32_e32 v209, v25, v87
	v_fmac_f32_e32 v210, v9, v87
	v_cvt_pk_bf16_f32 v203, v203, v1
	v_cvt_pk_bf16_f32 v204, v204, v1
	v_cvt_pk_bf16_f32 v205, v205, v1
	v_cvt_pk_bf16_f32 v206, v206, v1
	v_cvt_pk_bf16_f32 v207, v207, v1
	v_cvt_pk_bf16_f32 v208, v208, v1
	v_cvt_pk_bf16_f32 v209, v209, v1
	v_cvt_pk_bf16_f32 v210, v210, v1
	ds_write_b16 v200, v203 offset:2448
	ds_write_b16 v201, v204 offset:64
	ds_write_b16 v201, v205 offset:128
	ds_write_b16 v201, v206 offset:192
	ds_write_b16 v201, v207 offset:272
	ds_write_b16 v201, v208 offset:336
	ds_write_b16 v201, v209 offset:400
	ds_write_b16 v201, v210 offset:464
	s_waitcnt lgkmcnt(5)
; DI unsigned short f2bf1(float f) { return (unsigned short)(cvtpk(f, 0.f) & 0xffffu); }
; #define LDS_WAIT() asm volatile("s_waitcnt lgkmcnt(0)" ::: "memory")
; DI int crow(int r, int hi) { return (r & 3) + 8 * (r >> 2) + 4 * hi; }
; DI void nsa_stage_out(att::Core<128>& c, bf16_t* stg, float* ws, float fac, bool first, int r32, int hi) {
;     if (hi == 0) ws[r32] = fac;
;     LDS_WAIT();
; #pragma unroll
;     for (int r = 0; r < 16; ++r) { const int orow = att::crow(r, hi); const float f = ws[orow];
; #pragma unroll
;         for (int d0 = 0; d0 < 4; ++d0) { bf16_t* p = stg + orow * 136 + d0 * 32 + r32; float v = c.o[d0][r] * f; if (!first) v += bf2f(*p); *p = f2bf1(v); } }
;     LDS_WAIT();
; }
	ds_read_b32 v86, v182 offset:64
	ds_read_b32 v87, v182 offset:68
	ds_read_u16 v203, v201 offset:1632
	ds_read_u16 v204, v201 offset:1696
	ds_read_u16 v205, v201 offset:1760
	ds_read_u16 v206, v201 offset:1824
	ds_read_u16 v207, v201 offset:1904
	ds_read_u16 v208, v201 offset:1968
	ds_read_u16 v209, v201 offset:2032
	ds_read_u16 v210, v201 offset:2096
	s_waitcnt lgkmcnt(0)
	v_lshlrev_b32_e32 v203, 16, v203
	v_lshlrev_b32_e32 v204, 16, v204
	v_lshlrev_b32_e32 v205, 16, v205
	v_lshlrev_b32_e32 v206, 16, v206
	v_lshlrev_b32_e32 v207, 16, v207
	v_lshlrev_b32_e32 v208, 16, v208
	v_lshlrev_b32_e32 v209, 16, v209
	v_lshlrev_b32_e32 v210, 16, v210
	v_fmac_f32_e32 v203, v58, v86
	v_fmac_f32_e32 v204, v42, v86
	v_fmac_f32_e32 v205, v26, v86
	v_fmac_f32_e32 v206, v10, v86
	v_fmac_f32_e32 v207, v59, v87
	v_fmac_f32_e32 v208, v43, v87
	v_fmac_f32_e32 v209, v27, v87
	v_fmac_f32_e32 v210, v11, v87
	v_cvt_pk_bf16_f32 v203, v203, v1
	v_cvt_pk_bf16_f32 v204, v204, v1
	v_cvt_pk_bf16_f32 v205, v205, v1
	v_cvt_pk_bf16_f32 v206, v206, v1
	v_cvt_pk_bf16_f32 v207, v207, v1
	v_cvt_pk_bf16_f32 v208, v208, v1
	v_cvt_pk_bf16_f32 v209, v209, v1
	v_cvt_pk_bf16_f32 v210, v210, v1
	ds_write_b16 v201, v203 offset:1632
	ds_write_b16 v201, v204 offset:1696
	ds_write_b16 v201, v205 offset:1760
	ds_write_b16 v201, v206 offset:1824
	ds_write_b16 v201, v207 offset:1904
	ds_write_b16 v201, v208 offset:1968
	ds_write_b16 v201, v209 offset:2032
	ds_write_b16 v201, v210 offset:2096
	s_waitcnt lgkmcnt(5)
	ds_read_b32 v86, v182 offset:72
	ds_read_b32 v87, v182 offset:76
	ds_read_u16 v203, v201 offset:2176
	ds_read_u16 v204, v201 offset:2240
	ds_read_u16 v205, v201 offset:2304
	ds_read_u16 v206, v201 offset:2368
	ds_read_u16 v207, v201 offset:2448
	ds_read_u16 v208, v202 offset:64
	ds_read_u16 v209, v202 offset:128
	ds_read_u16 v210, v202 offset:192
	s_waitcnt lgkmcnt(0)
	v_lshlrev_b32_e32 v203, 16, v203
	v_lshlrev_b32_e32 v204, 16, v204
	v_lshlrev_b32_e32 v205, 16, v205
	v_lshlrev_b32_e32 v206, 16, v206
	v_lshlrev_b32_e32 v207, 16, v207
	v_lshlrev_b32_e32 v208, 16, v208
	v_lshlrev_b32_e32 v209, 16, v209
	v_lshlrev_b32_e32 v210, 16, v210
	v_fmac_f32_e32 v203, v60, v86
	v_fmac_f32_e32 v204, v44, v86
	v_fmac_f32_e32 v205, v28, v86
	v_fmac_f32_e32 v206, v12, v86
	v_fmac_f32_e32 v207, v61, v87
	v_fmac_f32_e32 v208, v45, v87
	v_fmac_f32_e32 v209, v29, v87
	v_fmac_f32_e32 v210, v13, v87
	v_cvt_pk_bf16_f32 v203, v203, v1
	v_cvt_pk_bf16_f32 v204, v204, v1
	v_cvt_pk_bf16_f32 v205, v205, v1
	v_cvt_pk_bf16_f32 v206, v206, v1
	v_cvt_pk_bf16_f32 v207, v207, v1
	v_cvt_pk_bf16_f32 v208, v208, v1
	v_cvt_pk_bf16_f32 v209, v209, v1
	v_cvt_pk_bf16_f32 v210, v210, v1
	ds_write_b16 v201, v203 offset:2176
	ds_write_b16 v201, v204 offset:2240
	ds_write_b16 v201, v205 offset:2304
	ds_write_b16 v201, v206 offset:2368
	ds_write_b16 v201, v207 offset:2448
	ds_write_b16 v202, v208 offset:64
	ds_write_b16 v202, v209 offset:128
	ds_write_b16 v202, v210 offset:192
	s_waitcnt lgkmcnt(5)
	ds_read_b32 v86, v182 offset:96
	ds_read_b32 v87, v182 offset:100
	ds_read_u16 v203, v202 offset:1360
	ds_read_u16 v204, v202 offset:1424
	ds_read_u16 v205, v202 offset:1488
	ds_read_u16 v206, v202 offset:1552
	ds_read_u16 v207, v202 offset:1632
	ds_read_u16 v208, v202 offset:1696
	ds_read_u16 v209, v202 offset:1760
	ds_read_u16 v210, v202 offset:1824
	s_waitcnt lgkmcnt(0)
	v_lshlrev_b32_e32 v203, 16, v203
	v_lshlrev_b32_e32 v204, 16, v204
	v_lshlrev_b32_e32 v205, 16, v205
	v_lshlrev_b32_e32 v206, 16, v206
	v_lshlrev_b32_e32 v207, 16, v207
	v_lshlrev_b32_e32 v208, 16, v208
	v_lshlrev_b32_e32 v209, 16, v209
	v_lshlrev_b32_e32 v210, 16, v210
	v_fmac_f32_e32 v203, v62, v86
	v_fmac_f32_e32 v204, v46, v86
	v_fmac_f32_e32 v205, v30, v86
	v_fmac_f32_e32 v206, v14, v86
	v_fmac_f32_e32 v207, v63, v87
	v_fmac_f32_e32 v208, v47, v87
	v_fmac_f32_e32 v209, v31, v87
	v_fmac_f32_e32 v210, v15, v87
	v_cvt_pk_bf16_f32 v203, v203, v1
	v_cvt_pk_bf16_f32 v204, v204, v1
	v_cvt_pk_bf16_f32 v205, v205, v1
	v_cvt_pk_bf16_f32 v206, v206, v1
	v_cvt_pk_bf16_f32 v207, v207, v1
	v_cvt_pk_bf16_f32 v208, v208, v1
	v_cvt_pk_bf16_f32 v209, v209, v1
	v_cvt_pk_bf16_f32 v210, v210, v1
	ds_write_b16 v202, v203 offset:1360
	ds_write_b16 v202, v204 offset:1424
	ds_write_b16 v202, v205 offset:1488
	ds_write_b16 v202, v206 offset:1552
	ds_write_b16 v202, v207 offset:1632
	ds_write_b16 v202, v208 offset:1696
	ds_write_b16 v202, v209 offset:1760
	ds_write_b16 v202, v210 offset:1824
	s_waitcnt lgkmcnt(5)
	ds_read_b32 v86, v182 offset:104
	ds_read_b32 v87, v182 offset:108
	ds_read_u16 v203, v202 offset:1904
	ds_read_u16 v204, v202 offset:1968
	ds_read_u16 v205, v202 offset:2032
	ds_read_u16 v206, v202 offset:2096
	ds_read_u16 v207, v202 offset:2176
	ds_read_u16 v208, v202 offset:2240
	ds_read_u16 v209, v202 offset:2304
	ds_read_u16 v210, v202 offset:2368
	s_waitcnt lgkmcnt(0)
; DI unsigned short f2bf1(float f) { return (unsigned short)(cvtpk(f, 0.f) & 0xffffu); }
; #define LDS_WAIT() asm volatile("s_waitcnt lgkmcnt(0)" ::: "memory")
; DI int crow(int r, int hi) { return (r & 3) + 8 * (r >> 2) + 4 * hi; }
; DI void nsa_stage_out(att::Core<128>& c, bf16_t* stg, float* ws, float fac, bool first, int r32, int hi) {
;     if (hi == 0) ws[r32] = fac;
;     LDS_WAIT();
; #pragma unroll
;     for (int r = 0; r < 16; ++r) { const int orow = att::crow(r, hi); const float f = ws[orow];
; #pragma unroll
;         for (int d0 = 0; d0 < 4; ++d0) { bf16_t* p = stg + orow * 136 + d0 * 32 + r32; float v = c.o[d0][r] * f; if (!first) v += bf2f(*p); *p = f2bf1(v); } }
;     LDS_WAIT();
; }
; DI void nsa_attention(int L2, char* lds, int vcu, int G, int tid, int wave, int lane) {
;     ...
;         {
;             att::core_reset<128>(c, att::M_INIT, 0.f);
;             SeqRange seq; seq.lo = qt - 8 < 0 ? 0 : qt - 8; seq.hi = qt;
;             MaskWin mk; mk.t = t; mk.w = 512; mk.tmin = t0; mk.tmax = t0 + 63;
	v_lshlrev_b32_e32 v203, 16, v203
	v_lshlrev_b32_e32 v204, 16, v204
	v_lshlrev_b32_e32 v205, 16, v205
	v_lshlrev_b32_e32 v206, 16, v206
	v_lshlrev_b32_e32 v207, 16, v207
	v_lshlrev_b32_e32 v208, 16, v208
	v_lshlrev_b32_e32 v209, 16, v209
	v_lshlrev_b32_e32 v210, 16, v210
	v_fmac_f32_e32 v203, v64, v86
	v_fmac_f32_e32 v204, v48, v86
	v_fmac_f32_e32 v205, v32, v86
	v_fmac_f32_e32 v206, v16, v86
	v_fmac_f32_e32 v207, v65, v87
	v_fmac_f32_e32 v208, v49, v87
	v_fmac_f32_e32 v209, v33, v87
	v_fmac_f32_e32 v210, v17, v87
	v_cvt_pk_bf16_f32 v203, v203, v1
	v_cvt_pk_bf16_f32 v204, v204, v1
	v_cvt_pk_bf16_f32 v205, v205, v1
	v_cvt_pk_bf16_f32 v206, v206, v1
	v_cvt_pk_bf16_f32 v207, v207, v1
	v_cvt_pk_bf16_f32 v208, v208, v1
	v_cvt_pk_bf16_f32 v209, v209, v1
	v_cvt_pk_bf16_f32 v210, v210, v1
	ds_write_b16 v202, v203 offset:1904
	ds_write_b16 v202, v204 offset:1968
	ds_write_b16 v202, v205 offset:2032
	ds_write_b16 v202, v206 offset:2096
	ds_write_b16 v202, v207 offset:2176
	ds_write_b16 v202, v208 offset:2240
	ds_write_b16 v202, v209 offset:2304
	ds_write_b16 v202, v210 offset:2368
	s_max_i32 s2, s91, 8
	s_add_i32 s92, s2, -8
	v_mov_b32_e32 v67, v165
	s_cmp_gt_i32 s92, s91
	v_mov_b32_e32 v66, v167
	v_mov_b32_e32 v68, 0
	v_mov_b32_e32 v50, 0
	v_mov_b32_e32 v34, 0
	v_mov_b32_e32 v18, 0
	v_mov_b32_e32 v51, 0
	v_mov_b32_e32 v35, 0
	v_mov_b32_e32 v19, 0
	v_mov_b32_e32 v3, 0
	v_mov_b32_e32 v52, 0
	v_mov_b32_e32 v36, 0
	v_mov_b32_e32 v20, 0
	v_mov_b32_e32 v4, 0
	v_mov_b32_e32 v53, 0
	v_mov_b32_e32 v37, 0
	v_mov_b32_e32 v21, 0
	v_mov_b32_e32 v5, 0
	v_mov_b32_e32 v54, 0
	v_mov_b32_e32 v38, 0
	v_mov_b32_e32 v22, 0
	v_mov_b32_e32 v6, 0
	v_mov_b32_e32 v55, 0
	v_mov_b32_e32 v39, 0
	v_mov_b32_e32 v23, 0
	v_mov_b32_e32 v7, 0
	v_mov_b32_e32 v56, 0
	v_mov_b32_e32 v40, 0
	v_mov_b32_e32 v24, 0
	v_mov_b32_e32 v8, 0
	v_mov_b32_e32 v57, 0
	v_mov_b32_e32 v41, 0
	v_mov_b32_e32 v25, 0
	v_mov_b32_e32 v9, 0
	v_mov_b32_e32 v58, 0
	v_mov_b32_e32 v42, 0
	v_mov_b32_e32 v26, 0
	v_mov_b32_e32 v10, 0
	v_mov_b32_e32 v59, 0
	v_mov_b32_e32 v43, 0
	v_mov_b32_e32 v27, 0
	v_mov_b32_e32 v11, 0
	v_mov_b32_e32 v60, 0
	v_mov_b32_e32 v44, 0
	v_mov_b32_e32 v28, 0
	v_mov_b32_e32 v12, 0
	v_mov_b32_e32 v61, 0
	v_mov_b32_e32 v45, 0
	v_mov_b32_e32 v29, 0
	v_mov_b32_e32 v13, 0
	v_mov_b32_e32 v62, 0
	v_mov_b32_e32 v46, 0
	v_mov_b32_e32 v30, 0
	v_mov_b32_e32 v14, 0
	v_mov_b32_e32 v63, 0
	v_mov_b32_e32 v47, 0
	v_mov_b32_e32 v31, 0
	v_mov_b32_e32 v15, 0
	v_mov_b32_e32 v64, 0
	v_mov_b32_e32 v48, 0
	v_mov_b32_e32 v32, 0
	v_mov_b32_e32 v16, 0
	v_mov_b32_e32 v65, 0
	v_mov_b32_e32 v49, 0
	v_mov_b32_e32 v33, 0
	s_waitcnt lgkmcnt(0)
	v_mov_b32_e32 v17, 0
	v_mov_b32_e32 v2, 0
	s_load_dwordx2 s[12:13], s[0:1], 0xc8
	s_waitcnt lgkmcnt(0)
	s_load_dwordx2 s[2:3], s[0:1], 0xc8
	s_waitcnt lgkmcnt(0)
	s_cbranch_scc1 .LBB0_898
; DI int v_rd_base(int lane) { return ((lane & 3) << 3) | (((lane >> 2) & 3) << 6) | (((lane >> 4) & 1) << 5) | (((lane >> 5) & 1) << 8); }
; #define LBAR() asm volatile("s_waitcnt lgkmcnt(0)\n\ts_barrier" ::: "memory")
; template <int D, bool PIPE, class Seq, class MaskF, class KX>
; DI void run_tiles(Core<D>& c, char* kv, float* ws, const bf16_t* Kg0, const bf16_t* Vg0, int pitch, const Seq& seq, const MaskF& mk, const KX& kx, int tid_, int lane_) {
;     ...
;     int t0; if (!seq.first(t0)) return;
;     const int vb0 = (int)(uintptr_t)(kv + 2 * KB) + v_rd_base(lane);
;     StgH<D> sk, sv;
;     if constexpr (!PIPE) {
;         stg_ld<D>(sk, Kg0 + (size_t)64 * t0 * pitch, pitch, tid); stg_ld<D>(sv, Vg0 + (size_t)64 * t0 * pitch, pitch, tid);
;         LBAR();
;         kx.apply(sk, t0, tid); stg_wrK<D>(sk, kv, tid); stg_wrV<D>(sv, kv + 2 * KB, tid);
;         LBAR();
	s_lshl_b64 s[14:15], s[48:49], 1
	s_add_u32 s4, s12, s14
	s_addc_u32 s5, s13, s15
	s_lshl_b32 s10, s56, 1
	s_add_u32 s4, s4, s10
	s_addc_u32 s5, s5, 0
	s_add_u32 s94, s4, 0x2fb02000
	s_addc_u32 s4, s5, 0
	s_add_u32 s2, s2, s14
	s_addc_u32 s3, s3, s15
	s_add_u32 s2, s2, s10
	s_addc_u32 s3, s3, 0
	s_add_u32 s5, s2, 0x2fb02400
	v_ashrrev_i32_e32 v3, 4, v67
	s_addc_u32 s85, s3, 0
	s_mul_i32 s14, s92, 0xa0000
	s_movk_i32 s15, 0x1400
	v_add_u32_e32 v9, 32, v3
	s_mul_hi_u32 s10, s92, 0xa0000
	s_add_u32 s2, s94, s14
	v_lshlrev_b32_e32 v8, 3, v67
	v_mad_i64_i32 v[4:5], s[12:13], v3, s15, 0
	v_mad_i64_i32 v[6:7], s[12:13], v9, s15, 0
	s_addc_u32 s3, s4, s10
	v_and_b32_e32 v2, 0x78, v8
	v_lshlrev_b64 v[170:171], 1, v[4:5]
	v_lshlrev_b64 v[172:173], 1, v[6:7]
	v_lshl_add_u64 v[4:5], s[2:3], 0, v[170:171]
	v_lshlrev_b32_e32 v0, 1, v2
	v_lshl_add_u64 v[6:7], s[2:3], 0, v[172:173]
	s_add_u32 s2, s5, s14
	v_lshl_add_u64 v[4:5], v[4:5], 0, v[0:1]
	s_addc_u32 s3, s85, s10
	v_lshl_add_u64 v[6:7], v[6:7], 0, v[0:1]
	global_load_dwordx4 v[98:101], v[4:5], off
	global_load_dwordx4 v[102:105], v[6:7], off
	v_lshl_add_u64 v[4:5], s[2:3], 0, v[170:171]
	v_lshl_add_u64 v[4:5], v[4:5], 0, v[0:1]
	v_lshl_add_u64 v[6:7], s[2:3], 0, v[172:173]
	v_lshl_add_u64 v[6:7], v[6:7], 0, v[0:1]
	global_load_dwordx4 v[106:109], v[4:5], off
	global_load_dwordx4 v[144:147], v[6:7], off
	v_ashrrev_i32_e32 v0, 5, v66
	v_and_b32_e32 v4, 31, v66
	v_lshlrev_b32_e32 v6, 4, v66
	v_and_b32_e32 v13, 0xfffff0, v3
	v_lshlrev_b32_e32 v14, 1, v3
	v_and_b32_e32 v12, 0xc0, v6
	v_lshlrev_b32_e32 v175, 8, v4
	v_and_b32_e32 v176, 0xf0, v6
	v_lshlrev_b32_e32 v177, 4, v0
	v_lshlrev_b32_e32 v203, 2, v0
	v_lshl_add_u32 v204, v4, 2, s11
	v_and_or_b32 v0, v14, 8, v13
	v_and_b32_e32 v4, 0xfffff0, v9
	v_lshlrev_b32_e32 v6, 1, v9
	v_lshrrev_b32_e32 v15, 1, v3
	v_bfe_u32 v8, v8, 5, 2
	v_and_b32_e32 v3, 3, v3
	v_lshrrev_b32_e32 v0, 1, v0
	v_and_or_b32 v4, v6, 8, v4
	v_lshlrev_b32_e32 v10, 4, v67
	v_and_b32_e32 v11, 0xf0, v67
	s_movk_i32 s2, 0xf0
	v_and_or_b32 v3, v15, 4, v3
	v_or_b32_e32 v0, v0, v8
	v_lshrrev_b32_e32 v4, 1, v4
	v_lshlrev_b32_e32 v7, 1, v66
	v_bitop3_b32 v11, v10, v11, s2 bitop3:0x6c
	v_and_b32_e32 v16, 48, v10
	s_movk_i32 s2, 0xff00
	v_lshlrev_b32_e32 v3, 6, v3
	v_lshlrev_b32_e32 v0, 9, v0
	v_or_b32_e32 v4, v4, v8
	v_lshlrev_b32_e32 v5, 3, v66
	v_and_b32_e32 v7, 32, v7
	v_and_or_b32 v205, v10, s2, v11
	s_movk_i32 s2, 0x118
	v_or3_b32 v212, v0, v3, v16
	v_lshlrev_b32_e32 v0, 9, v4
	v_and_or_b32 v5, v5, s2, v7
	v_add_u32_e32 v7, 0, v205
	v_or3_b32 v213, v0, v3, v16
	s_add_i32 s90, s86, 0xfffffe3f
	s_add_i32 s2, 0, 0x8000
	v_add_u32_e32 v4, 0, v212
	v_add_u32_e32 v0, 0, v213
	s_waitcnt lgkmcnt(0)
	s_barrier
	s_cmp_lg_u32 s2, -1
	v_writelane_b32 v255, s80, 22
	s_cselect_b32 s2, s2, 0
	v_mov_b32_e32 v50, v1
	v_mov_b32_e32 v51, v1
	v_writelane_b32 v255, s79, 25
	v_add3_u32 v214, v12, s2, v5
	v_mov_b32_e32 v52, v1
	v_mov_b32_e32 v53, v1
	v_mov_b32_e32 v54, v1
	v_mov_b32_e32 v55, v1
	s_waitcnt vmcnt(3)
	ds_write_b128 v7, v[98:101]
	s_waitcnt vmcnt(2)
	ds_write_b128 v7, v[102:105] offset:8192
	s_waitcnt vmcnt(1)
	ds_write_b128 v4, v[106:109] offset:32768
	s_waitcnt vmcnt(0)
	ds_write_b128 v0, v[144:147] offset:32768
	s_waitcnt lgkmcnt(0)
	s_barrier
	v_mov_b32_e32 v56, v1
	v_mov_b32_e32 v57, v1
	v_mov_b32_e32 v58, v1
	v_mov_b32_e32 v59, v1
	v_mov_b32_e32 v60, v1
	v_mov_b32_e32 v61, v1
	v_mov_b32_e32 v62, v1
	v_mov_b32_e32 v63, v1
	v_mov_b32_e32 v64, v1
	v_mov_b32_e32 v65, v1
	v_lshlrev_b32_e32 v0, 1, v2
	v_mov_b64_e32 v[34:35], v[50:51]
	v_mov_b64_e32 v[18:19], v[50:51]
	v_mov_b64_e32 v[2:3], v[50:51]
	v_writelane_b32 v255, s78, 21
	s_mov_b32 s84, 0x42b504f3
	v_cmp_gt_u32_e64 s[12:13], 32, v66
	v_add_u32_e32 v174, 0xfffffe00, v169
	v_add_u32_e32 v206, 0x60, v177
	v_add_u32_e32 v207, 0x80, v177
	v_add_u32_e32 v208, 0xa0, v177
	v_add_u32_e32 v209, 0xc0, v177
	v_add_u32_e32 v210, 0xe0, v177
	v_add_u32_e32 v211, s11, v177
	s_mov_b32 s10, 0
	v_mov_b32_e32 v216, 0
	v_mov_b32_e32 v215, 0xc6ea6000
	v_mov_b64_e32 v[36:37], v[52:53]
	v_mov_b64_e32 v[38:39], v[54:55]
	v_mov_b64_e32 v[40:41], v[56:57]
	v_mov_b64_e32 v[42:43], v[58:59]
	v_mov_b64_e32 v[44:45], v[60:61]
	v_mov_b64_e32 v[46:47], v[62:63]
	v_mov_b64_e32 v[48:49], v[64:65]
	v_mov_b64_e32 v[20:21], v[52:53]
	v_mov_b64_e32 v[22:23], v[54:55]
	v_mov_b64_e32 v[24:25], v[56:57]
	v_mov_b64_e32 v[26:27], v[58:59]
	v_mov_b64_e32 v[28:29], v[60:61]
	v_mov_b64_e32 v[30:31], v[62:63]
	v_mov_b64_e32 v[32:33], v[64:65]
	v_mov_b64_e32 v[4:5], v[52:53]
	v_mov_b64_e32 v[6:7], v[54:55]
	v_mov_b64_e32 v[8:9], v[56:57]
	v_mov_b64_e32 v[10:11], v[58:59]
	v_mov_b64_e32 v[12:13], v[60:61]
	v_mov_b64_e32 v[14:15], v[62:63]
	v_mov_b64_e32 v[16:17], v[64:65]
